# v14 + dv256 pass prologues: Q-fragment loads (global, into QK scratch registers) overlap the first K/V LDS-DMA issue; wait and LDS writes moved behind the 12th DMA
# baseline (speedup 1.0000x reference)
; #define LAS __attribute__((address_space(3)))
; #define F_TID() tid_of(F.wave)
; __device__ __forceinline__ void attn_pass_dv256(const bf16_t* __restrict__ Qb, const bf16_t* __restrict__ Kh, const bf16_t* __restrict__ Vh, int qpos0,
;                                                 LAS unsigned char* lds, f32x16 (&o)[8], float& l_out, int wave_) {
;   const int tid = tid_of(wave_), wid = wave_, lane = tid & 63, r32 = lane & 31, hi = lane >> 5;
;   LAS unsigned char* K_lds = lds + K2_OFF;
;   LAS float* al_l = (LAS float*)(lds + WS2_OFF) + wid * 64 + 32;
;   const LAS float* tbl = (const LAS float*)(lds + TBL2_OFF);
;   float m_reg = -1e30f, l_reg = 0;
; #pragma unroll
;   for (int d = 0; d < 8; ++d) o[d] = f32x16{};
;   bf16x8 qr[4];
;   LAS unsigned char* qf = lds + Q2_OFF + wid * 4096;
;   const bf16_t* Qw = Qb + (size_t)(wid * 32 + r32) * LDX + hi * 8;
; #pragma unroll
;   for (int d0 = 0; d0 < 4; ++d0) qr[d0] = *(const bf16x8*)(Qw + d0 * 16);
; #pragma unroll
;   for (int d0 = 4; d0 < 8; ++d0) *(LAS bf16x8*)(qf + ((d0 - 4) * 64 + lane) * 16) = *(const bf16x8*)(Qw + d0 * 16);
;   const unsigned ldsb = (unsigned)(uintptr_t)lds;
;   const unsigned vb0 = ldsb + V2_OFF + v_rd_base(lane);
;   const int krow = 4 * wid + (lane >> 4);
;   const unsigned voffK = (unsigned)(krow * (LDX * 2) + (((lane & 15) ^ (krow & 15)) << 4));
;   const int vst_ = 2 * wid + (lane >> 5), vkk = (vst_ >> 2) * 8 + ((lane >> 2) & 7), vk = (vkk & ~0xC) | ((vkk & 4) << 1) | ((vkk & 8) >> 1);
;   const unsigned voffV = (unsigned)(vk * (LDX * 2) + ((vst_ & 3) * 4 + (lane & 3)) * 16);
;   const int qw0 = qpos0 + wid * 32, qme = qw0 + r32;
;   constexpr int NT = SEQ / KVBLK;
;     ...
;   f32x16 p0, p1; float mn, al, cadd; bf16x8 pa0, pa1, pa2, pa3;
;   DMA_KV(0, 0); DMA_KV(1, 1);
;   asm volatile("s_waitcnt vmcnt(6)" ::: "memory"); BARL();
; template <int PH> __global__ void __launch_bounds__(512, 2) fwd(Params P, int L0, int L1) {
;     ...
;                 const int qb = unit & 15, bh = unit >> 4, h = bh & 7, b = bh >> 3; const size_t rows0 = (size_t)b * SEQ + qb * 256, krow0 = (size_t)b * SEQ;
;                 { const int t_ = F_TID(); if (t_ < 257) tbl[t_] = INP(12)[t5_bucket(t_ - 128) * 8 + h] * LOG2E; }
;                 __syncthreads();
;                 bf16_t* Ow = BUF1 + (rows0 + wid * 32) * 2048 + h * 256;
;                 {
;                     f32x16 o[8]; float l; float rli[16];
.LBB0_373:
	s_or_b64 exec, exec, s[4:5]
	s_lshr_b32 s4, s26, 4
	s_and_b32 s4, s4, 7
	s_ashr_i32 s6, s26, 7
	s_lshl_b32 s27, s4, 9
	s_and_b32 s16, s21, 0xf00
	v_readlane_b32 s4, v254, 56
	s_ashr_i32 s7, s6, 31
	s_lshl_b32 s8, s26, 8
	v_readlane_b32 s38, v252, 12
	s_sub_i32 s30, s4, s16
	s_lshl_b64 s[4:5], s[6:7], 12
	s_and_b32 s8, s8, 0xf00
	v_readlane_b32 s39, v252, 13
	s_or_b32 s4, s4, s8
	s_mov_b64 s[18:19], s[38:39]
	s_mov_b64 s[10:11], s[38:39]
	s_waitcnt lgkmcnt(0)
	s_barrier
	s_lshl_b32 s36, s24, 8
	s_lshl_b64 s[8:9], s[4:5], 11
	s_lshl_b64 s[12:13], s[4:5], 12
	s_add_u32 s10, s10, s12
	s_addc_u32 s11, s11, s13
	s_lshl_b32 s17, s24, 9
	s_mov_b64 s[24:25], s[38:39]
	s_mov_b64 s[12:13], s[38:39]
	v_mov_b32_e32 v20, v220
	v_readlane_b32 s48, v254, 55
	v_and_b32_e32 v22, 31, v20
	s_add_u32 s10, s10, s17
	v_or_b32_e32 v184, s48, v22
	s_addc_u32 s11, s11, 0
	v_bfe_u32 v21, v20, 5, 1
	v_lshlrev_b64 v[0:1], 12, v[184:185]
	v_lshl_add_u64 v[0:1], s[10:11], 0, v[0:1]
	v_lshlrev_b32_e32 v184, 4, v21
	v_lshl_add_u64 v[16:17], v[0:1], 0, v[184:185]
	s_mov_b64 s[10:11], 0x19000000
	v_lshl_add_u64 v[18:19], v[16:17], 0, s[10:11]
	global_load_dwordx4 v[192:195], v[18:19], off offset:128
	global_load_dwordx4 v[196:199], v[18:19], off offset:160
	global_load_dwordx4 v[200:203], v[18:19], off offset:192
	global_load_dwordx4 v[204:207], v[18:19], off offset:224
	v_bfe_u32 v26, v20, 4, 2
	v_readlane_b32 s10, v253, 19
	v_and_b32_e32 v23, 63, v20
	v_lshlrev_b32_e32 v24, 3, v20
	v_lshlrev_b32_e32 v25, 1, v20
	v_bfe_u32 v27, v20, 2, 2
	v_lshrrev_b32_e32 v28, 1, v20
	v_lshlrev_b32_e32 v29, 4, v20
	v_or_b32_e32 v31, s10, v26
	v_bitop3_b32 v20, v26, v20, s10 bitop3:0x36
	v_readlane_b32 s10, v253, 22
	v_lshlrev_b32_e32 v30, 4, v23
	v_and_b32_e32 v26, 8, v28
	v_or_b32_e32 v28, s10, v21
	v_readlane_b32 s10, v253, 23
	v_lshlrev_b32_e32 v31, 12, v31
	v_lshlrev_b32_e32 v20, 4, v20
	v_add_u32_e32 v234, s10, v30
	v_readlane_b32 s10, v253, 20
	s_movk_i32 s49, 0xf0
	v_and_b32_e32 v32, 48, v29
	v_or3_b32 v26, v27, v26, s10
	s_lshl_b64 s[10:11], s[6:7], 23
	s_lshl_b64 s[6:7], s[6:7], 24
	s_add_u32 s40, s24, s6
	s_mov_b32 s24, 0x19000000
	v_add_co_u32_e32 v16, vcc, s24, v16
	s_addc_u32 s41, s25, s7
	s_nop 0
	v_addc_co_u32_e32 v17, vcc, 0, v17, vcc
	global_load_dwordx4 v[160:163], v[16:17], off
	global_load_dwordx4 v[164:167], v[18:19], off offset:96
	global_load_dwordx4 v[168:171], v[18:19], off offset:32
	global_load_dwordx4 v[172:175], v[18:19], off offset:64
	s_add_u32 s31, s40, s17
	s_addc_u32 s45, s41, 0
	s_add_u32 s24, s31, 0x21000000
	s_addc_u32 s25, s45, 0
	s_add_u32 s43, s12, s6
	s_addc_u32 s44, s13, s7
	s_add_u32 s17, s43, s17
	s_addc_u32 s46, s44, 0
	s_add_u32 s12, s17, 0x29000000
	s_addc_u32 s13, s46, 0
	v_and_or_b32 v235, v20, s49, v31
	s_add_u32 s38, s31, 0x21020000
	v_lshl_or_b32 v27, v28, 6, v32
	s_addc_u32 s39, s45, 0
	v_lshl_or_b32 v236, v26, 12, v27
	s_waitcnt lgkmcnt(0)
	s_mov_b32 m0, s80
	s_nop 0
	global_load_lds_dwordx4 v235, s[24:25]
	s_mov_b32 m0, s81
	s_nop 0
	global_load_lds_dwordx4 v235, s[38:39]
	v_and_b32_e32 v0, 0xf0, v29
	s_mov_b32 m0, s76
	s_nop 0
	global_load_lds_dwordx4 v236, s[12:13]
	s_add_u32 s12, s17, 0x29020000
	s_addc_u32 s13, s46, 0
	s_mov_b32 m0, s89
	s_nop 0
	global_load_lds_dwordx4 v236, s[12:13]
	s_add_u32 s12, s17, 0x29000100
	s_addc_u32 s13, s46, 0
	s_mov_b32 m0, s1
	s_nop 0
	global_load_lds_dwordx4 v236, s[12:13]
	s_add_u32 s12, s17, 0x29020100
	s_addc_u32 s13, s46, 0
	s_mov_b32 m0, s69
	s_nop 0
	global_load_lds_dwordx4 v236, s[12:13]
	s_add_u32 s12, s31, 0x21040000
	s_addc_u32 s13, s45, 0
	s_add_u32 s24, s17, 0x29040000
	s_addc_u32 s25, s46, 0
	s_mov_b32 m0, s29
	s_nop 0
	global_load_lds_dwordx4 v235, s[12:13]
	s_add_u32 s12, s31, 0x21060000
	s_addc_u32 s13, s45, 0
	s_mov_b32 m0, s88
	s_nop 0
	global_load_lds_dwordx4 v235, s[12:13]
	s_mov_b32 m0, s22
	s_nop 0
	global_load_lds_dwordx4 v236, s[24:25]
	s_add_u32 s12, s17, 0x29060000
	s_addc_u32 s13, s46, 0
	s_mov_b32 m0, s2
	s_nop 0
	global_load_lds_dwordx4 v236, s[12:13]
	s_add_u32 s12, s17, 0x29040100
	s_addc_u32 s13, s46, 0
	s_mov_b32 m0, s14
	s_nop 0
	global_load_lds_dwordx4 v236, s[12:13]
	s_add_u32 s12, s17, 0x29060100
	s_addc_u32 s13, s46, 0
	s_mov_b32 m0, s15
	s_nop 0
	global_load_lds_dwordx4 v236, s[12:13]
	s_waitcnt vmcnt(12)
	ds_write_b128 v234, v[192:195]
	ds_write_b128 v234, v[196:199] offset:1024
	ds_write_b128 v234, v[200:203] offset:2048
	ds_write_b128 v234, v[204:207] offset:3072
	s_movk_i32 s12, 0x60
	v_bitop3_b32 v242, v184, v0, s12 bitop3:0x36
	s_movk_i32 s12, 0x80
	v_bitop3_b32 v243, v184, v0, s12 bitop3:0x36
	s_movk_i32 s12, 0xa0
	v_bitop3_b32 v244, v184, v0, s12 bitop3:0x36
	s_movk_i32 s12, 0xc0
	s_waitcnt vmcnt(6)
	v_and_b32_e32 v1, 0x118, v24
	v_bitop3_b32 v245, v184, v0, s12 bitop3:0x36
	s_movk_i32 s12, 0xe0
	v_and_b32_e32 v30, 0xc0, v30
	s_waitcnt lgkmcnt(0)
	s_barrier
; #define LAS __attribute__((address_space(3)))
; __device__ __forceinline__ int v_rd_base(int lane) { return ((lane & 3) << 3) | (((lane >> 2) & 3) << 6) | (((lane >> 4) & 1) << 5) | (((lane >> 5) & 1) << 8); }
; __device__ __forceinline__ void attn_pass_dv256(const bf16_t* __restrict__ Qb, const bf16_t* __restrict__ Kh, const bf16_t* __restrict__ Vh, int qpos0,
;                                                 LAS unsigned char* lds, f32x16 (&o)[8], float& l_out, int wave_) {
;     ...
;   float m_reg = -1e30f, l_reg = 0;
; #pragma unroll
;   for (int d = 0; d < 8; ++d) o[d] = f32x16{};
;   bf16x8 qr[4];
;   LAS unsigned char* qf = lds + Q2_OFF + wid * 4096;
;   const bf16_t* Qw = Qb + (size_t)(wid * 32 + r32) * LDX + hi * 8;
; #pragma unroll
;   for (int d0 = 0; d0 < 4; ++d0) qr[d0] = *(const bf16x8*)(Qw + d0 * 16);
; #pragma unroll
;   for (int d0 = 4; d0 < 8; ++d0) *(LAS bf16x8*)(qf + ((d0 - 4) * 64 + lane) * 16) = *(const bf16x8*)(Qw + d0 * 16);
;   const unsigned ldsb = (unsigned)(uintptr_t)lds;
;   const unsigned vb0 = ldsb + V2_OFF + v_rd_base(lane);
;   const int krow = 4 * wid + (lane >> 4);
;   const unsigned voffK = (unsigned)(krow * (LDX * 2) + (((lane & 15) ^ (krow & 15)) << 4));
;   const int vst_ = 2 * wid + (lane >> 5), vkk = (vst_ >> 2) * 8 + ((lane >> 2) & 7), vk = (vkk & ~0xC) | ((vkk & 4) << 1) | ((vkk & 8) >> 1);
;   const unsigned voffV = (unsigned)(vk * (LDX * 2) + ((vst_ & 3) * 4 + (lane & 3)) * 16);
;   const int qw0 = qpos0 + wid * 32, qme = qw0 + r32;
;   constexpr int NT = SEQ / KVBLK;
	v_bitop3_b32 v240, v184, v0, 32 bitop3:0x36
	v_bitop3_b32 v241, v184, v0, 64 bitop3:0x36
	v_bitop3_b32 v246, v184, v0, s12 bitop3:0x36
	v_and_or_b32 v0, v25, 32, v1
	s_add_i32 s31, s48, s16
	v_mov_b32_e32 v96, v185
	v_mov_b32_e32 v97, v185
	v_lshl_add_u32 v237, v22, 8, s23
	v_lshlrev_b32_e32 v2, 2, v21
	v_cmp_gt_u32_e64 s[38:39], 32, v23
	v_lshl_add_u32 v238, v22, 2, s59
	v_bitop3_b32 v239, v184, v29, s49 bitop3:0x78
	v_add3_u32 v247, v30, 0, v0
	v_add_u32_e32 v0, s31, v22
	v_mov_b32_e32 v98, v185
	v_mov_b32_e32 v99, v185
	v_mov_b32_e32 v100, v185
	v_mov_b32_e32 v101, v185
	v_mov_b32_e32 v102, v185
	v_mov_b32_e32 v103, v185
	v_mov_b32_e32 v104, v185
	v_mov_b32_e32 v105, v185
	v_mov_b32_e32 v106, v185
	v_mov_b32_e32 v107, v185
	v_mov_b32_e32 v108, v185
	v_mov_b32_e32 v109, v185
	v_mov_b32_e32 v110, v185
	v_mov_b32_e32 v111, v185
	v_mov_b32_e32 v250, 0
	v_mov_b64_e32 v[64:65], v[96:97]
	v_mov_b64_e32 v[32:33], v[96:97]
	v_mov_b64_e32 v[16:17], v[96:97]
	v_mov_b64_e32 v[218:219], 0x3ff
	v_mov_b64_e32 v[188:189], 0x400
	v_mov_b64_e32 v[186:187], 0x15ff
	s_mov_b32 s37, 0
	v_sub_u32_e32 v248, v2, v0
	v_mov_b32_e32 v249, 0xf149f2ca
	v_mov_b64_e32 v[66:67], v[98:99]
	v_mov_b64_e32 v[68:69], v[100:101]
	v_mov_b64_e32 v[70:71], v[102:103]
	v_mov_b64_e32 v[72:73], v[104:105]
	v_mov_b64_e32 v[74:75], v[106:107]
	v_mov_b64_e32 v[76:77], v[108:109]
	v_mov_b64_e32 v[78:79], v[110:111]
	v_mov_b64_e32 v[34:35], v[98:99]
	v_mov_b64_e32 v[36:37], v[100:101]
	v_mov_b64_e32 v[38:39], v[102:103]
	v_mov_b64_e32 v[40:41], v[104:105]
	v_mov_b64_e32 v[42:43], v[106:107]
	v_mov_b64_e32 v[44:45], v[108:109]
	v_mov_b64_e32 v[46:47], v[110:111]
	v_mov_b64_e32 v[18:19], v[98:99]
	v_mov_b64_e32 v[20:21], v[100:101]
	v_mov_b64_e32 v[22:23], v[102:103]
	v_mov_b64_e32 v[24:25], v[104:105]
	v_mov_b64_e32 v[26:27], v[106:107]
	v_mov_b64_e32 v[28:29], v[108:109]
	v_mov_b64_e32 v[30:31], v[110:111]
	s_mov_b32 s45, 0
	v_mov_b32_e32 v112, 0
	v_mov_b32_e32 v113, v250
	v_mov_b32_e32 v114, v250
	v_mov_b32_e32 v115, v250
	v_mov_b32_e32 v116, v250
	v_mov_b32_e32 v117, v250
	v_mov_b32_e32 v118, v250
	v_mov_b32_e32 v119, v250
	v_mov_b32_e32 v120, v250
	v_mov_b32_e32 v121, v250
	v_mov_b32_e32 v122, v250
	v_mov_b32_e32 v123, v250
	v_mov_b32_e32 v124, v250
	v_mov_b32_e32 v125, v250
	v_mov_b32_e32 v126, v250
	v_mov_b32_e32 v127, v250
	v_mov_b32_e32 v80, 0
	v_mov_b32_e32 v81, v250
	v_mov_b32_e32 v82, v250
	v_mov_b32_e32 v83, v250
	v_mov_b32_e32 v84, v250
	v_mov_b32_e32 v85, v250
	v_mov_b32_e32 v86, v250
	v_mov_b32_e32 v87, v250
	v_mov_b32_e32 v88, v250
	v_mov_b32_e32 v89, v250
	v_mov_b32_e32 v90, v250
	v_mov_b32_e32 v91, v250
	v_mov_b32_e32 v92, v250
	v_mov_b32_e32 v93, v250
	v_mov_b32_e32 v94, v250
	v_mov_b32_e32 v95, v250
	v_mov_b32_e32 v48, 0
	v_mov_b32_e32 v49, v250
	v_mov_b32_e32 v50, v250
	v_mov_b32_e32 v51, v250
	v_mov_b32_e32 v52, v250
	v_mov_b32_e32 v53, v250
	v_mov_b32_e32 v54, v250
	v_mov_b32_e32 v55, v250
	v_mov_b32_e32 v56, v250
	v_mov_b32_e32 v57, v250
	v_mov_b32_e32 v58, v250
	v_mov_b32_e32 v59, v250
	v_mov_b32_e32 v60, v250
	v_mov_b32_e32 v61, v250
	v_mov_b32_e32 v62, v250
	v_mov_b32_e32 v63, v250
	v_mov_b32_e32 v0, 0
	v_mov_b32_e32 v1, v250
	v_mov_b32_e32 v2, v250
	v_mov_b32_e32 v3, v250
	v_mov_b32_e32 v4, v250
	v_mov_b32_e32 v5, v250
	v_mov_b32_e32 v6, v250
	v_mov_b32_e32 v7, v250
	v_mov_b32_e32 v8, v250
	v_mov_b32_e32 v9, v250
	v_mov_b32_e32 v10, v250
	v_mov_b32_e32 v11, v250
	v_mov_b32_e32 v12, v250
	v_mov_b32_e32 v13, v250
	v_mov_b32_e32 v14, v250
	v_mov_b32_e32 v15, v250

; #define LAS __attribute__((address_space(3)))
; __device__ __forceinline__ int opqv(int x) { asm volatile("" : "+v"(x)); return x; }
; __device__ __forceinline__ int crow(int r, int hi) { return (r & 3) + 8 * (r >> 2) + 4 * hi; }
; __device__ __forceinline__ unsigned cvtpk(float lo, float hi) { const f32x2 v = {lo, hi}; return __builtin_bit_cast(unsigned, __builtin_convertvector(v, bf16x2_t)); }
; __device__ __forceinline__ void row_inv_l(float l_reg, LAS unsigned char* lds, int wid, int r32_, int hi_, float (&rli)[16], int ws_off = WS_OFF) {
;   const int r32 = opqv(r32_), hi = opqv(hi_);
;   LAS float* li_l = (LAS float*)(lds + ws_off) + wid * 64;
;   if (hi == 0) li_l[r32] = l_reg; asm volatile("s_waitcnt lgkmcnt(0)" ::: "memory");
; #pragma unroll
;   for (int r = 0; r < 16; ++r) rli[r] = __builtin_amdgcn_rcpf(li_l[crow(r, hi)]);
; }
; __device__ __forceinline__ void stage_tile(const f32x16* o, LAS unsigned char* stg, int r32_, int hi_) {
;   const int r32 = opqv(r32_), hi = opqv(hi_);
; #pragma unroll
;   for (int d0 = 0; d0 < 4; ++d0)
; #pragma unroll
;     for (int r = 0; r < 16; r += 2) { const unsigned w = cvtpk(o[d0][r], o[d0][r + 1]);
;       *(LAS bf16_t*)(stg + crow(r, hi) * 256 + (32 * d0 + r32) * 2) = (bf16_t)(w & 0xffffu); *(LAS bf16_t*)(stg + crow(r + 1, hi) * 256 + (32 * d0 + r32) * 2) = (bf16_t)(w >> 16); }
;   asm volatile("s_waitcnt lgkmcnt(0)" ::: "memory");
; }
; template <int PH> __global__ void __launch_bounds__(512, 2) fwd(Params P, int L0, int L1) {
;     ...
;                     att::row_inv_l(l, F.lds, wid, r32, hi, rli, att::WS2_OFF);
; #pragma unroll
;                     for (int d = 0; d < 8; ++d)
; #pragma unroll
;                         for (int r = 0; r < 16; ++r) o[d][r] *= rli[r];
;                     att::stage_tile(o, stg, r32, hi); att::flush_tile<0>(stg, Ow, nullptr, lane);
.LBB0_388:
	s_or_b64 exec, exec, s[12:13]
	v_readlane_b32 s12, v253, 28
	s_waitcnt lgkmcnt(0)
	v_readlane_b32 s17, v254, 55
	s_add_u32 s4, s4, s17
	v_lshl_add_u32 v142, v129, 4, s12
	ds_read_b128 v[128:131], v142
	ds_read_b128 v[132:135], v142 offset:32
	v_readlane_b32 s12, v253, 21
	s_addc_u32 s5, s5, 0
	s_lshl_b64 s[4:5], s[4:5], 12
	s_waitcnt lgkmcnt(1)
	v_rcp_f32_e32 v146, v128
	v_rcp_f32_e32 v147, v129
	v_rcp_f32_e32 v140, v130
	v_rcp_f32_e32 v141, v131
	ds_read_b128 v[128:131], v142 offset:64
	ds_read_b128 v[142:145], v142 offset:96
	s_waitcnt lgkmcnt(2)
	v_rcp_f32_e32 v136, v134
	v_rcp_f32_e32 v137, v135
	v_rcp_f32_e32 v138, v132
	s_waitcnt lgkmcnt(1)
	v_rcp_f32_e32 v134, v128
	v_rcp_f32_e32 v135, v129
	s_waitcnt lgkmcnt(0)
	v_rcp_f32_e32 v128, v144
	v_rcp_f32_e32 v129, v145
	v_rcp_f32_e32 v139, v133
	v_rcp_f32_e32 v132, v130
	v_rcp_f32_e32 v133, v131
	v_pk_mul_f32 v[158:159], v[128:129], v[78:79]
	v_pk_mul_f32 v[78:79], v[146:147], v[32:33]
	v_pk_mul_f32 v[32:33], v[146:147], v[48:49]
	v_mov_b32_e32 v48, v232
	v_mov_b32_e32 v49, v233
	v_pk_mul_f32 v[96:97], v[146:147], v[96:97]
	v_pk_mul_f32 v[98:99], v[140:141], v[98:99]
	v_lshlrev_b32_e32 v49, 10, v49
	v_lshlrev_b32_e32 v48, 1, v48
	v_rcp_f32_e32 v130, v142
	v_rcp_f32_e32 v131, v143
	v_pk_mul_f32 v[100:101], v[138:139], v[100:101]
	v_pk_mul_f32 v[142:143], v[146:147], v[64:65]
	v_pk_mul_f32 v[64:65], v[140:141], v[34:35]
	v_pk_mul_f32 v[34:35], v[140:141], v[50:51]
	v_cvt_pk_bf16_f32 v50, v96, v97
	v_add3_u32 v48, s12, v48, v49
	v_cvt_pk_bf16_f32 v49, v98, v99
	v_pk_mul_f32 v[102:103], v[136:137], v[102:103]
	ds_write_b16 v48, v50
	ds_write_b16_d16_hi v48, v50 offset:256
	ds_write_b16 v48, v49 offset:512
	ds_write_b16_d16_hi v48, v49 offset:768
	v_cvt_pk_bf16_f32 v49, v100, v101
	v_pk_mul_f32 v[104:105], v[134:135], v[104:105]
	ds_write_b16 v48, v49 offset:2048
	ds_write_b16_d16_hi v48, v49 offset:2304
	v_cvt_pk_bf16_f32 v49, v102, v103
	v_pk_mul_f32 v[106:107], v[132:133], v[106:107]
	ds_write_b16 v48, v49 offset:2560
	ds_write_b16_d16_hi v48, v49 offset:2816
	v_cvt_pk_bf16_f32 v49, v104, v105
	v_pk_mul_f32 v[108:109], v[130:131], v[108:109]
	ds_write_b16 v48, v49 offset:4096
	ds_write_b16_d16_hi v48, v49 offset:4352
	v_cvt_pk_bf16_f32 v49, v106, v107
	v_pk_mul_f32 v[110:111], v[128:129], v[110:111]
	ds_write_b16 v48, v49 offset:4608
	ds_write_b16_d16_hi v48, v49 offset:4864
	v_cvt_pk_bf16_f32 v49, v108, v109
	v_pk_mul_f32 v[112:113], v[146:147], v[112:113]
	ds_write_b16 v48, v49 offset:6144
	ds_write_b16_d16_hi v48, v49 offset:6400
	v_cvt_pk_bf16_f32 v49, v110, v111
	v_pk_mul_f32 v[114:115], v[140:141], v[114:115]
	ds_write_b16 v48, v49 offset:6656
	ds_write_b16_d16_hi v48, v49 offset:6912
	v_cvt_pk_bf16_f32 v49, v112, v113
	v_pk_mul_f32 v[116:117], v[138:139], v[116:117]
	ds_write_b16 v48, v49 offset:64
	ds_write_b16_d16_hi v48, v49 offset:320
	v_cvt_pk_bf16_f32 v49, v114, v115
	v_pk_mul_f32 v[118:119], v[136:137], v[118:119]
	ds_write_b16 v48, v49 offset:576
	ds_write_b16_d16_hi v48, v49 offset:832
	v_cvt_pk_bf16_f32 v49, v116, v117
	v_pk_mul_f32 v[120:121], v[134:135], v[120:121]
	ds_write_b16 v48, v49 offset:2112
	ds_write_b16_d16_hi v48, v49 offset:2368
	v_cvt_pk_bf16_f32 v49, v118, v119
	v_pk_mul_f32 v[122:123], v[132:133], v[122:123]
	ds_write_b16 v48, v49 offset:2624
	ds_write_b16_d16_hi v48, v49 offset:2880
	v_cvt_pk_bf16_f32 v49, v120, v121
	v_pk_mul_f32 v[124:125], v[130:131], v[124:125]
	ds_write_b16 v48, v49 offset:4160
	ds_write_b16_d16_hi v48, v49 offset:4416
	v_cvt_pk_bf16_f32 v49, v122, v123
	v_pk_mul_f32 v[126:127], v[128:129], v[126:127]
	ds_write_b16 v48, v49 offset:4672
	ds_write_b16_d16_hi v48, v49 offset:4928
	v_cvt_pk_bf16_f32 v49, v124, v125
	ds_write_b16 v48, v49 offset:6208
	ds_write_b16_d16_hi v48, v49 offset:6464
	v_cvt_pk_bf16_f32 v49, v126, v127
	v_pk_mul_f32 v[144:145], v[140:141], v[66:67]
	ds_write_b16 v48, v49 offset:6720
	ds_write_b16_d16_hi v48, v49 offset:6976
	v_cvt_pk_bf16_f32 v49, v142, v143
	v_pk_mul_f32 v[148:149], v[138:139], v[68:69]
	ds_write_b16 v48, v49 offset:128
	ds_write_b16_d16_hi v48, v49 offset:384
	v_cvt_pk_bf16_f32 v49, v144, v145
	v_pk_mul_f32 v[150:151], v[136:137], v[70:71]
	ds_write_b16 v48, v49 offset:640
	ds_write_b16_d16_hi v48, v49 offset:896
	v_cvt_pk_bf16_f32 v49, v148, v149
	v_pk_mul_f32 v[152:153], v[134:135], v[72:73]
	ds_write_b16 v48, v49 offset:2176
	ds_write_b16_d16_hi v48, v49 offset:2432
	v_cvt_pk_bf16_f32 v49, v150, v151
	v_pk_mul_f32 v[154:155], v[132:133], v[74:75]
	ds_write_b16 v48, v49 offset:2688
	ds_write_b16_d16_hi v48, v49 offset:2944
	v_cvt_pk_bf16_f32 v49, v152, v153
	v_pk_mul_f32 v[156:157], v[130:131], v[76:77]
	ds_write_b16 v48, v49 offset:4224
	ds_write_b16_d16_hi v48, v49 offset:4480
	v_cvt_pk_bf16_f32 v49, v154, v155
	ds_write_b16 v48, v49 offset:4736
	ds_write_b16_d16_hi v48, v49 offset:4992
	v_cvt_pk_bf16_f32 v49, v156, v157
	v_pk_mul_f32 v[80:81], v[146:147], v[80:81]
	ds_write_b16 v48, v49 offset:6272
	ds_write_b16_d16_hi v48, v49 offset:6528
	v_cvt_pk_bf16_f32 v49, v158, v159
	v_pk_mul_f32 v[82:83], v[140:141], v[82:83]
	ds_write_b16 v48, v49 offset:6784
	ds_write_b16_d16_hi v48, v49 offset:7040
	v_cvt_pk_bf16_f32 v49, v80, v81
	v_pk_mul_f32 v[84:85], v[138:139], v[84:85]
	ds_write_b16 v48, v49 offset:192
	ds_write_b16_d16_hi v48, v49 offset:448
	v_cvt_pk_bf16_f32 v49, v82, v83
	v_pk_mul_f32 v[86:87], v[136:137], v[86:87]
	ds_write_b16 v48, v49 offset:704
	ds_write_b16_d16_hi v48, v49 offset:960
	v_cvt_pk_bf16_f32 v49, v84, v85
	v_pk_mul_f32 v[88:89], v[134:135], v[88:89]
	ds_write_b16 v48, v49 offset:2240
	ds_write_b16_d16_hi v48, v49 offset:2496
	v_cvt_pk_bf16_f32 v49, v86, v87
	v_pk_mul_f32 v[90:91], v[132:133], v[90:91]
	ds_write_b16 v48, v49 offset:2752
	ds_write_b16_d16_hi v48, v49 offset:3008
	v_cvt_pk_bf16_f32 v49, v88, v89
	v_pk_mul_f32 v[92:93], v[130:131], v[92:93]
	ds_write_b16 v48, v49 offset:4288
	ds_write_b16_d16_hi v48, v49 offset:4544
	v_cvt_pk_bf16_f32 v49, v90, v91
	v_pk_mul_f32 v[94:95], v[128:129], v[94:95]
	ds_write_b16 v48, v49 offset:4800
	ds_write_b16_d16_hi v48, v49 offset:5056
	v_cvt_pk_bf16_f32 v49, v92, v93
	ds_write_b16 v48, v49 offset:6336
	ds_write_b16_d16_hi v48, v49 offset:6592
	v_cvt_pk_bf16_f32 v49, v94, v95
	v_pk_mul_f32 v[72:73], v[132:133], v[42:43]
	v_pk_mul_f32 v[42:43], v[132:133], v[58:59]
	ds_write_b16 v48, v49 offset:6848
	ds_write_b16_d16_hi v48, v49 offset:7104
	v_mov_b32_e32 v58, v231
	s_waitcnt lgkmcnt(0)
; #define LAS __attribute__((address_space(3)))
; __device__ __forceinline__ u32x4 pack8(f32x4 a, f32x4 b) { u32x4 w; w.x = cvt_pk_bf16(a[0], a[1]); w.y = cvt_pk_bf16(a[2], a[3]); w.z = cvt_pk_bf16(b[0], b[1]); w.w = cvt_pk_bf16(b[2], b[3]); return w; }
; __device__ __forceinline__ float bf_lo(unsigned w) { return __uint_as_float(w << 16); }
; __device__ __forceinline__ float bf_hi(unsigned w) { return __uint_as_float(w & 0xffff0000u); }
; __device__ __forceinline__ int opqv(int x) { asm volatile("" : "+v"(x)); return x; }
; template <int M> __device__ __forceinline__ void flush_tile(LAS unsigned char* stg, bf16_t* Ob, LAS float* ssq_l, int lane_) {
;   const int lane = opqv(lane_);
; #pragma unroll
;   for (int it = 0; it < 8; ++it) { const int idx = it * 64 + lane, row = idx >> 4, ch = idx & 15;
;     u32x4 w = *(const LAS u32x4*)(stg + row * 256 + ch * 16);
;     if constexpr (M > 0) {
;       f32x4 a = {bf_lo(w.x), bf_hi(w.x), bf_lo(w.y), bf_hi(w.y)}, b = {bf_lo(w.z), bf_hi(w.z), bf_lo(w.w), bf_hi(w.w)};
;       float t = (a[0] * a[0] + a[1] * a[1]) + (a[2] * a[2] + a[3] * a[3]) + (b[0] * b[0] + b[1] * b[1]) + (b[2] * b[2] + b[3] * b[3]);
;       t = row16_sum(t);
;       if constexpr (M == 1) { if (ch == 0) ssq_l[row] = t; }
;       else { const float sc = rsqrtf((ssq_l[row] + t) * (1.0f / 256.0f) + 1e-6f); w = pack8(a * sc, b * sc);
;         asm volatile("s_waitcnt lgkmcnt(0)" ::: "memory"); if (ch == 0) ssq_l[row] = sc; }
;     }
;     *(u32x4*)(Ob + (size_t)row * LDX + ch * 8) = w; }
;   asm volatile("s_waitcnt lgkmcnt(0)" ::: "memory");
; }
; template <int PH> __global__ void __launch_bounds__(512, 2) fwd(Params P, int L0, int L1) {
;     ...
;                     att::stage_tile(o, stg, r32, hi); att::flush_tile<0>(stg, Ow, nullptr, lane);
;                     att::stage_tile(o + 4, stg, r32, hi); att::flush_tile<0>(stg, Ow + 128, nullptr, lane);
	s_add_u32 s4, s18, s4
	v_lshlrev_b32_e32 v48, 4, v58
	v_and_b32_e32 v184, 0xf0, v48
	s_addc_u32 s5, s19, s5
	s_lshl_b32 s16, s36, 1
	v_pk_mul_f32 v[66:67], v[138:139], v[36:37]
	v_pk_mul_f32 v[36:37], v[138:139], v[52:53]
	v_add_u32_e32 v59, s12, v184
	v_ashrrev_i32_e32 v52, 4, v58
	s_add_u32 s4, s4, s16
	v_lshl_add_u32 v48, v52, 8, v59
	s_addc_u32 s5, s5, 0
	ds_read_b128 v[48:51], v48
	s_add_u32 s4, s4, 0x10000000
	s_addc_u32 s5, s5, 0
	v_ashrrev_i32_e32 v53, 31, v52
	v_pk_mul_f32 v[68:69], v[136:137], v[38:39]
	v_pk_mul_f32 v[38:39], v[136:137], v[54:55]
	v_lshl_add_u64 v[54:55], s[4:5], 0, v[184:185]
	v_lshlrev_b64 v[52:53], 12, v[52:53]
	v_lshl_add_u64 v[52:53], v[54:55], 0, v[52:53]
	s_waitcnt lgkmcnt(0)
	flat_store_dwordx4 v[52:53], v[48:51]
	v_pk_mul_f32 v[70:71], v[134:135], v[40:41]
	v_pk_mul_f32 v[40:41], v[134:135], v[56:57]
	v_add_u32_e32 v48, 64, v58
	v_ashrrev_i32_e32 v52, 4, v48
	v_lshl_add_u32 v48, v52, 8, v59
	ds_read_b128 v[48:51], v48
	v_ashrrev_i32_e32 v53, 31, v52
	v_pk_mul_f32 v[56:57], v[140:141], v[2:3]
	v_lshlrev_b64 v[2:3], 12, v[52:53]
	v_lshl_add_u64 v[2:3], v[54:55], 0, v[2:3]
	s_waitcnt lgkmcnt(0)
	flat_store_dwordx4 v[2:3], v[48:51]
	v_add_u32_e32 v2, 0x80, v58
	v_ashrrev_i32_e32 v2, 4, v2
	v_lshl_add_u32 v3, v2, 8, v59
	ds_read_b128 v[48:51], v3
	v_ashrrev_i32_e32 v3, 31, v2
	v_lshlrev_b64 v[2:3], 12, v[2:3]
	v_lshl_add_u64 v[2:3], v[54:55], 0, v[2:3]
	v_pk_mul_f32 v[52:53], v[138:139], v[4:5]
	s_waitcnt lgkmcnt(0)
	flat_store_dwordx4 v[2:3], v[48:51]
	v_add_u32_e32 v2, 0xc0, v58
	v_pk_mul_f32 v[74:75], v[130:131], v[44:45]
	v_ashrrev_i32_e32 v48, 4, v2
	v_lshl_add_u32 v2, v48, 8, v59
	ds_read_b128 v[2:5], v2
	v_ashrrev_i32_e32 v49, 31, v48
	v_lshlrev_b64 v[48:49], 12, v[48:49]
	v_lshl_add_u64 v[48:49], v[54:55], 0, v[48:49]
	v_pk_mul_f32 v[76:77], v[128:129], v[46:47]
	s_waitcnt lgkmcnt(0)
	flat_store_dwordx4 v[48:49], v[2:5]
	v_pk_mul_f32 v[44:45], v[130:131], v[60:61]
	v_pk_mul_f32 v[46:47], v[128:129], v[62:63]
	v_add_u32_e32 v2, 0x100, v58
	v_ashrrev_i32_e32 v48, 4, v2
	v_lshl_add_u32 v2, v48, 8, v59
	ds_read_b128 v[2:5], v2
	v_ashrrev_i32_e32 v49, 31, v48
	v_lshlrev_b64 v[48:49], 12, v[48:49]
	v_lshl_add_u64 v[48:49], v[54:55], 0, v[48:49]
	v_pk_mul_f32 v[16:17], v[146:147], v[16:17]
	s_waitcnt lgkmcnt(0)
	flat_store_dwordx4 v[48:49], v[2:5]
	v_pk_mul_f32 v[18:19], v[140:141], v[18:19]
	v_pk_mul_f32 v[20:21], v[138:139], v[20:21]
	v_add_u32_e32 v2, 0x140, v58
	v_ashrrev_i32_e32 v48, 4, v2
	v_lshl_add_u32 v2, v48, 8, v59
	ds_read_b128 v[2:5], v2
	v_ashrrev_i32_e32 v49, 31, v48
	v_lshlrev_b64 v[48:49], 12, v[48:49]
	v_lshl_add_u64 v[48:49], v[54:55], 0, v[48:49]
	v_pk_mul_f32 v[22:23], v[136:137], v[22:23]
	s_waitcnt lgkmcnt(0)
	flat_store_dwordx4 v[48:49], v[2:5]
	v_pk_mul_f32 v[24:25], v[134:135], v[24:25]
	v_pk_mul_f32 v[26:27], v[132:133], v[26:27]
	v_add_u32_e32 v2, 0x180, v58
	v_ashrrev_i32_e32 v48, 4, v2
	v_lshl_add_u32 v2, v48, 8, v59
	ds_read_b128 v[2:5], v2
	v_ashrrev_i32_e32 v49, 31, v48
	v_lshlrev_b64 v[48:49], 12, v[48:49]
	v_lshl_add_u64 v[48:49], v[54:55], 0, v[48:49]
	v_pk_mul_f32 v[28:29], v[130:131], v[28:29]
	s_waitcnt lgkmcnt(0)
	flat_store_dwordx4 v[48:49], v[2:5]
	v_pk_mul_f32 v[30:31], v[128:129], v[30:31]
	v_pk_mul_f32 v[0:1], v[146:147], v[0:1]
	v_add_u32_e32 v2, 0x1c0, v58
	v_ashrrev_i32_e32 v48, 4, v2
	v_lshl_add_u32 v2, v48, 8, v59
	ds_read_b128 v[2:5], v2
	v_ashrrev_i32_e32 v49, 31, v48
	v_lshlrev_b64 v[48:49], 12, v[48:49]
	v_lshl_add_u64 v[48:49], v[54:55], 0, v[48:49]
	v_cvt_pk_bf16_f32 v0, v0, v1
	s_waitcnt lgkmcnt(0)
	flat_store_dwordx4 v[48:49], v[2:5]
	s_waitcnt lgkmcnt(0)
	v_pk_mul_f32 v[6:7], v[136:137], v[6:7]
	v_pk_mul_f32 v[8:9], v[134:135], v[8:9]
	v_mov_b32_e32 v2, v232
	v_mov_b32_e32 v3, v233
	v_cvt_pk_bf16_f32 v4, v78, v79
	v_lshlrev_b32_e32 v3, 10, v3
	v_lshlrev_b32_e32 v2, 1, v2
	v_add3_u32 v2, s12, v2, v3
	v_cvt_pk_bf16_f32 v3, v64, v65
	ds_write_b16 v2, v4
	ds_write_b16_d16_hi v2, v4 offset:256
	ds_write_b16 v2, v3 offset:512
	ds_write_b16_d16_hi v2, v3 offset:768
	v_cvt_pk_bf16_f32 v3, v66, v67
	ds_write_b16 v2, v3 offset:2048
	ds_write_b16_d16_hi v2, v3 offset:2304
	v_cvt_pk_bf16_f32 v3, v68, v69
	ds_write_b16 v2, v3 offset:2560
	ds_write_b16_d16_hi v2, v3 offset:2816
	v_cvt_pk_bf16_f32 v3, v70, v71
	ds_write_b16 v2, v3 offset:4096
	ds_write_b16_d16_hi v2, v3 offset:4352
	v_cvt_pk_bf16_f32 v3, v72, v73
	ds_write_b16 v2, v3 offset:4608
	ds_write_b16_d16_hi v2, v3 offset:4864
	v_cvt_pk_bf16_f32 v3, v74, v75
	ds_write_b16 v2, v3 offset:6144
	ds_write_b16_d16_hi v2, v3 offset:6400
	v_cvt_pk_bf16_f32 v3, v76, v77
	ds_write_b16 v2, v3 offset:6656
	ds_write_b16_d16_hi v2, v3 offset:6912
	v_cvt_pk_bf16_f32 v3, v32, v33
	ds_write_b16 v2, v3 offset:64
	ds_write_b16_d16_hi v2, v3 offset:320
	v_cvt_pk_bf16_f32 v3, v34, v35
	ds_write_b16 v2, v3 offset:576
	ds_write_b16_d16_hi v2, v3 offset:832
	v_cvt_pk_bf16_f32 v3, v36, v37
	ds_write_b16 v2, v3 offset:2112
	ds_write_b16_d16_hi v2, v3 offset:2368
	v_cvt_pk_bf16_f32 v3, v38, v39
	ds_write_b16 v2, v3 offset:2624
	ds_write_b16_d16_hi v2, v3 offset:2880
	v_cvt_pk_bf16_f32 v3, v40, v41
	ds_write_b16 v2, v3 offset:4160
	ds_write_b16_d16_hi v2, v3 offset:4416
	v_cvt_pk_bf16_f32 v3, v42, v43
	ds_write_b16 v2, v3 offset:4672
	ds_write_b16_d16_hi v2, v3 offset:4928
	v_cvt_pk_bf16_f32 v3, v44, v45
	ds_write_b16 v2, v3 offset:6208
	ds_write_b16_d16_hi v2, v3 offset:6464
	v_cvt_pk_bf16_f32 v3, v46, v47
	ds_write_b16 v2, v3 offset:6720
	ds_write_b16_d16_hi v2, v3 offset:6976
	v_cvt_pk_bf16_f32 v3, v16, v17
	ds_write_b16 v2, v3 offset:128
	ds_write_b16_d16_hi v2, v3 offset:384
	v_cvt_pk_bf16_f32 v3, v18, v19
	ds_write_b16 v2, v3 offset:640
; #define LAS __attribute__((address_space(3)))
; __device__ __forceinline__ u32x4 pack8(f32x4 a, f32x4 b) { u32x4 w; w.x = cvt_pk_bf16(a[0], a[1]); w.y = cvt_pk_bf16(a[2], a[3]); w.z = cvt_pk_bf16(b[0], b[1]); w.w = cvt_pk_bf16(b[2], b[3]); return w; }
; __device__ __forceinline__ float bf_lo(unsigned w) { return __uint_as_float(w << 16); }
; __device__ __forceinline__ float bf_hi(unsigned w) { return __uint_as_float(w & 0xffff0000u); }
; __device__ __forceinline__ int opqv(int x) { asm volatile("" : "+v"(x)); return x; }
; __device__ __forceinline__ void stage_tile(const f32x16* o, LAS unsigned char* stg, int r32_, int hi_) {
;   const int r32 = opqv(r32_), hi = opqv(hi_);
; #pragma unroll
;   for (int d0 = 0; d0 < 4; ++d0)
; #pragma unroll
;     for (int r = 0; r < 16; r += 2) { const unsigned w = cvtpk(o[d0][r], o[d0][r + 1]);
;       *(LAS bf16_t*)(stg + crow(r, hi) * 256 + (32 * d0 + r32) * 2) = (bf16_t)(w & 0xffffu); *(LAS bf16_t*)(stg + crow(r + 1, hi) * 256 + (32 * d0 + r32) * 2) = (bf16_t)(w >> 16); }
;   asm volatile("s_waitcnt lgkmcnt(0)" ::: "memory");
; }
; template <int M> __device__ __forceinline__ void flush_tile(LAS unsigned char* stg, bf16_t* Ob, LAS float* ssq_l, int lane_) {
;   const int lane = opqv(lane_);
; #pragma unroll
;   for (int it = 0; it < 8; ++it) { const int idx = it * 64 + lane, row = idx >> 4, ch = idx & 15;
;     u32x4 w = *(const LAS u32x4*)(stg + row * 256 + ch * 16);
;     if constexpr (M > 0) {
;       f32x4 a = {bf_lo(w.x), bf_hi(w.x), bf_lo(w.y), bf_hi(w.y)}, b = {bf_lo(w.z), bf_hi(w.z), bf_lo(w.w), bf_hi(w.w)};
;       float t = (a[0] * a[0] + a[1] * a[1]) + (a[2] * a[2] + a[3] * a[3]) + (b[0] * b[0] + b[1] * b[1]) + (b[2] * b[2] + b[3] * b[3]);
;       t = row16_sum(t);
;       if constexpr (M == 1) { if (ch == 0) ssq_l[row] = t; }
;       else { const float sc = rsqrtf((ssq_l[row] + t) * (1.0f / 256.0f) + 1e-6f); w = pack8(a * sc, b * sc);
;         asm volatile("s_waitcnt lgkmcnt(0)" ::: "memory"); if (ch == 0) ssq_l[row] = sc; }
;     }
;     *(u32x4*)(Ob + (size_t)row * LDX + ch * 8) = w; }
;   asm volatile("s_waitcnt lgkmcnt(0)" ::: "memory");
; }
; template <int PH> __global__ void __launch_bounds__(512, 2) fwd(Params P, int L0, int L1) {
;     ...
;                     att::stage_tile(o + 4, stg, r32, hi); att::flush_tile<0>(stg, Ow + 128, nullptr, lane);
;                     __syncthreads();
	ds_write_b16_d16_hi v2, v3 offset:896
	v_cvt_pk_bf16_f32 v3, v20, v21
	ds_write_b16 v2, v3 offset:2176
	ds_write_b16_d16_hi v2, v3 offset:2432
	v_cvt_pk_bf16_f32 v3, v22, v23
	ds_write_b16 v2, v3 offset:2688
	ds_write_b16_d16_hi v2, v3 offset:2944
	v_cvt_pk_bf16_f32 v3, v24, v25
	ds_write_b16 v2, v3 offset:4224
	ds_write_b16_d16_hi v2, v3 offset:4480
	v_cvt_pk_bf16_f32 v3, v26, v27
	ds_write_b16 v2, v3 offset:4736
	ds_write_b16_d16_hi v2, v3 offset:4992
	v_cvt_pk_bf16_f32 v3, v28, v29
	ds_write_b16 v2, v3 offset:6272
	ds_write_b16_d16_hi v2, v3 offset:6528
	v_cvt_pk_bf16_f32 v3, v30, v31
	ds_write_b16 v2, v3 offset:6784
	ds_write_b16_d16_hi v2, v3 offset:7040
	ds_write_b16 v2, v0 offset:192
	ds_write_b16_d16_hi v2, v0 offset:448
	v_cvt_pk_bf16_f32 v0, v56, v57
	ds_write_b16 v2, v0 offset:704
	ds_write_b16_d16_hi v2, v0 offset:960
	v_cvt_pk_bf16_f32 v0, v52, v53
	ds_write_b16 v2, v0 offset:2240
	ds_write_b16_d16_hi v2, v0 offset:2496
	v_cvt_pk_bf16_f32 v0, v6, v7
	v_pk_mul_f32 v[10:11], v[132:133], v[10:11]
	ds_write_b16 v2, v0 offset:2752
	ds_write_b16_d16_hi v2, v0 offset:3008
	v_cvt_pk_bf16_f32 v0, v8, v9
	v_pk_mul_f32 v[12:13], v[130:131], v[12:13]
	ds_write_b16 v2, v0 offset:4288
	ds_write_b16_d16_hi v2, v0 offset:4544
	v_cvt_pk_bf16_f32 v0, v10, v11
	v_pk_mul_f32 v[14:15], v[128:129], v[14:15]
	ds_write_b16 v2, v0 offset:4800
	ds_write_b16_d16_hi v2, v0 offset:5056
	v_cvt_pk_bf16_f32 v0, v12, v13
	ds_write_b16 v2, v0 offset:6336
	ds_write_b16_d16_hi v2, v0 offset:6592
	v_cvt_pk_bf16_f32 v0, v14, v15
	ds_write_b16 v2, v0 offset:6848
	ds_write_b16_d16_hi v2, v0 offset:7104
	v_mov_b32_e32 v8, v231
	s_waitcnt lgkmcnt(0)
	v_readlane_b32 s24, v252, 12
	v_lshlrev_b32_e32 v0, 4, v8
	v_and_b32_e32 v184, 0xf0, v0
	v_add_u32_e32 v9, s12, v184
	v_ashrrev_i32_e32 v4, 4, v8
	v_lshl_add_u32 v0, v4, 8, v9
	ds_read_b128 v[0:3], v0
	v_ashrrev_i32_e32 v5, 31, v4
	v_lshl_add_u64 v[6:7], s[4:5], 0, v[184:185]
	v_lshlrev_b64 v[4:5], 12, v[4:5]
	v_lshl_add_u64 v[4:5], v[6:7], 0, v[4:5]
	s_waitcnt lgkmcnt(0)
	flat_store_dwordx4 v[4:5], v[0:3] offset:256
	v_readlane_b32 s25, v252, 13
	s_mov_b64 s[12:13], s[24:25]
	v_add_u32_e32 v0, 64, v8
	v_ashrrev_i32_e32 v4, 4, v0
	v_lshl_add_u32 v0, v4, 8, v9
	ds_read_b128 v[0:3], v0
	v_ashrrev_i32_e32 v5, 31, v4
	v_lshlrev_b64 v[4:5], 12, v[4:5]
	v_lshl_add_u64 v[4:5], v[6:7], 0, v[4:5]
	s_lshl_b64 s[8:9], s[8:9], 1
	s_waitcnt lgkmcnt(0)
	flat_store_dwordx4 v[4:5], v[0:3] offset:256
	v_mov_b32_e32 v18, v220
	s_movk_i32 s40, 0xf0
	v_add_u32_e32 v0, 0x80, v8
	v_ashrrev_i32_e32 v4, 4, v0
	v_lshl_add_u32 v0, v4, 8, v9
	ds_read_b128 v[0:3], v0
	v_ashrrev_i32_e32 v5, 31, v4
	v_lshlrev_b64 v[4:5], 12, v[4:5]
	v_lshl_add_u64 v[4:5], v[6:7], 0, v[4:5]
	v_mov_b32_e32 v250, 0
	s_waitcnt lgkmcnt(0)
	flat_store_dwordx4 v[4:5], v[0:3] offset:256
	v_mov_b32_e32 v249, 0xf149f2ca
	v_mov_b32_e32 v22, v250
	v_add_u32_e32 v0, 0xc0, v8
	v_ashrrev_i32_e32 v4, 4, v0
	v_lshl_add_u32 v0, v4, 8, v9
	ds_read_b128 v[0:3], v0
	v_ashrrev_i32_e32 v5, 31, v4
	v_lshlrev_b64 v[4:5], 12, v[4:5]
	v_lshl_add_u64 v[4:5], v[6:7], 0, v[4:5]
	v_mov_b32_e32 v23, v250
	s_waitcnt lgkmcnt(0)
	flat_store_dwordx4 v[4:5], v[0:3] offset:256
	v_mov_b32_e32 v24, v250
	v_mov_b32_e32 v25, v250
	v_add_u32_e32 v0, 0x100, v8
	v_ashrrev_i32_e32 v4, 4, v0
	v_lshl_add_u32 v0, v4, 8, v9
	ds_read_b128 v[0:3], v0
	v_ashrrev_i32_e32 v5, 31, v4
	v_lshlrev_b64 v[4:5], 12, v[4:5]
	v_lshl_add_u64 v[4:5], v[6:7], 0, v[4:5]
	v_mov_b32_e32 v26, v250
	s_waitcnt lgkmcnt(0)
	flat_store_dwordx4 v[4:5], v[0:3] offset:256
	v_mov_b32_e32 v27, v250
	v_mov_b32_e32 v28, v250
	v_add_u32_e32 v0, 0x140, v8
	v_ashrrev_i32_e32 v4, 4, v0
	v_lshl_add_u32 v0, v4, 8, v9
	ds_read_b128 v[0:3], v0
	v_ashrrev_i32_e32 v5, 31, v4
	v_lshlrev_b64 v[4:5], 12, v[4:5]
	v_lshl_add_u64 v[4:5], v[6:7], 0, v[4:5]
	v_mov_b32_e32 v29, v250
	s_waitcnt lgkmcnt(0)
	flat_store_dwordx4 v[4:5], v[0:3] offset:256
	v_mov_b32_e32 v30, v250
	v_mov_b32_e32 v31, v250
	v_add_u32_e32 v0, 0x180, v8
	v_ashrrev_i32_e32 v4, 4, v0
	v_lshl_add_u32 v0, v4, 8, v9
	ds_read_b128 v[0:3], v0
	v_ashrrev_i32_e32 v5, 31, v4
	v_lshlrev_b64 v[4:5], 12, v[4:5]
	v_lshl_add_u64 v[4:5], v[6:7], 0, v[4:5]
	v_mov_b32_e32 v64, 0
	s_waitcnt lgkmcnt(0)
	flat_store_dwordx4 v[4:5], v[0:3] offset:256
	v_mov_b32_e32 v65, v250
	v_mov_b32_e32 v66, v250
	v_add_u32_e32 v0, 0x1c0, v8
	v_ashrrev_i32_e32 v4, 4, v0
	v_lshl_add_u32 v0, v4, 8, v9
	ds_read_b128 v[0:3], v0
	v_ashrrev_i32_e32 v5, 31, v4
	v_lshlrev_b64 v[4:5], 12, v[4:5]
	v_lshl_add_u64 v[4:5], v[6:7], 0, v[4:5]
	v_mov_b32_e32 v67, v250
	s_waitcnt lgkmcnt(0)
	flat_store_dwordx4 v[4:5], v[0:3] offset:256
	s_waitcnt lgkmcnt(0)
	s_waitcnt lgkmcnt(0)
	s_barrier
; #define LAS __attribute__((address_space(3)))
; __device__ __forceinline__ int tid_of(int wave) { return opqv(wave * 64 + (int)__builtin_amdgcn_mbcnt_hi(~0u, __builtin_amdgcn_mbcnt_lo(~0u, 0u))); }
; __device__ __forceinline__ int v_rd_base(int lane) { return ((lane & 3) << 3) | (((lane >> 2) & 3) << 6) | (((lane >> 4) & 1) << 5) | (((lane >> 5) & 1) << 8); }
; __device__ __forceinline__ void attn_pass_dv256(const bf16_t* __restrict__ Qb, const bf16_t* __restrict__ Kh, const bf16_t* __restrict__ Vh, int qpos0,
;                                                 LAS unsigned char* lds, f32x16 (&o)[8], float& l_out, int wave_) {
;   const int tid = tid_of(wave_), wid = wave_, lane = tid & 63, r32 = lane & 31, hi = lane >> 5;
;   LAS unsigned char* K_lds = lds + K2_OFF;
;   LAS float* al_l = (LAS float*)(lds + WS2_OFF) + wid * 64 + 32;
;   const LAS float* tbl = (const LAS float*)(lds + TBL2_OFF);
;   float m_reg = -1e30f, l_reg = 0;
; #pragma unroll
;   for (int d = 0; d < 8; ++d) o[d] = f32x16{};
;   bf16x8 qr[4];
;   LAS unsigned char* qf = lds + Q2_OFF + wid * 4096;
;   const bf16_t* Qw = Qb + (size_t)(wid * 32 + r32) * LDX + hi * 8;
; #pragma unroll
;   for (int d0 = 0; d0 < 4; ++d0) qr[d0] = *(const bf16x8*)(Qw + d0 * 16);
; #pragma unroll
;   for (int d0 = 4; d0 < 8; ++d0) *(LAS bf16x8*)(qf + ((d0 - 4) * 64 + lane) * 16) = *(const bf16x8*)(Qw + d0 * 16);
;   const unsigned ldsb = (unsigned)(uintptr_t)lds;
;   const unsigned vb0 = ldsb + V2_OFF + v_rd_base(lane);
;   const int krow = 4 * wid + (lane >> 4);
;   const unsigned voffK = (unsigned)(krow * (LDX * 2) + (((lane & 15) ^ (krow & 15)) << 4));
;   const int vst_ = 2 * wid + (lane >> 5), vkk = (vst_ >> 2) * 8 + ((lane >> 2) & 7), vk = (vkk & ~0xC) | ((vkk & 4) << 1) | ((vkk & 8) >> 1);
;   const unsigned voffV = (unsigned)(vk * (LDX * 2) + ((vst_ & 3) * 4 + (lane & 3)) * 16);
;   const int qw0 = qpos0 + wid * 32, qme = qw0 + r32;
;   constexpr int NT = SEQ / KVBLK;
;     ...
;   f32x16 p0, p1; float mn, al, cadd; bf16x8 pa0, pa1, pa2, pa3;
;   DMA_KV(0, 0); DMA_KV(1, 1);
;   asm volatile("s_waitcnt vmcnt(6)" ::: "memory"); BARL();
; template <int PH> __global__ void __launch_bounds__(512, 2) fwd(Params P, int L0, int L1) {
;     ...
;                     att::attn_pass_dv256(DQ + rows0 * 2048 + (2 * h + 1) * 128, DK + krow0 * 2048 + (2 * h + 1) * 128, DV + krow0 * 2048 + h * 256, qb * 256, F.lds, o, l, F.wave);
	s_add_u32 s8, s12, s8
	s_addc_u32 s9, s13, s9
	s_add_u32 s18, s8, s16
	s_addc_u32 s19, s9, 0
	s_mov_b64 s[8:9], s[24:25]
	s_mov_b64 s[12:13], s[24:25]
	s_lshl_b64 s[10:11], s[10:11], 1
	v_and_b32_e32 v20, 31, v18
	v_or_b32_e32 v184, s17, v20
	v_bfe_u32 v19, v18, 5, 1
	v_lshlrev_b64 v[0:1], 12, v[184:185]
	v_lshl_add_u64 v[0:1], s[18:19], 0, v[0:1]
	v_lshlrev_b32_e32 v184, 4, v19
	v_lshl_add_u64 v[0:1], v[0:1], 0, v[184:185]
	s_mov_b64 s[18:19], 0x19000000
	v_lshl_add_u64 v[16:17], v[0:1], 0, s[18:19]
	global_load_dwordx4 v[192:195], v[16:17], off offset:384
	global_load_dwordx4 v[196:199], v[16:17], off offset:416
	global_load_dwordx4 v[200:203], v[16:17], off offset:448
	global_load_dwordx4 v[204:207], v[16:17], off offset:480
	global_load_dwordx4 v[160:163], v[16:17], off offset:256
	global_load_dwordx4 v[164:167], v[16:17], off offset:288
	global_load_dwordx4 v[168:171], v[16:17], off offset:320
	global_load_dwordx4 v[172:175], v[16:17], off offset:352
	s_add_u32 s17, s8, s10
	s_addc_u32 s18, s9, s11
	s_add_u32 s24, s17, s16
	s_addc_u32 s25, s18, 0
	s_add_u32 s18, s24, 0x21000100
	s_addc_u32 s19, s25, 0
	s_add_u32 s10, s12, s10
	s_addc_u32 s11, s13, s11
	v_and_b32_e32 v21, 63, v18
	s_add_u32 s36, s10, s16
	v_lshlrev_b32_e32 v16, 4, v21
	v_readlane_b32 s16, v253, 23
	s_addc_u32 s37, s11, 0
	s_add_u32 s10, s36, 0x29000000
	v_add_u32_e32 v234, s16, v16
	s_waitcnt lgkmcnt(0)
	v_bfe_u32 v3, v18, 4, 2
	v_readlane_b32 s16, v253, 19
	s_addc_u32 s11, s37, 0
	v_lshlrev_b32_e32 v5, 4, v18
	v_or_b32_e32 v4, s16, v3
	v_bitop3_b32 v3, v3, v18, s16 bitop3:0x36
	v_lshlrev_b32_e32 v4, 12, v4
	v_lshlrev_b32_e32 v3, 4, v3
	v_and_or_b32 v235, v3, s40, v4
	v_lshrrev_b32_e32 v4, 1, v18
	v_bfe_u32 v3, v18, 2, 2
	v_and_b32_e32 v4, 8, v4
	v_readlane_b32 s16, v253, 20
	v_and_b32_e32 v6, 48, v5
	v_lshlrev_b32_e32 v0, 3, v18
	v_or3_b32 v3, v3, v4, s16
	v_readlane_b32 s16, v253, 22
	v_lshlrev_b32_e32 v2, 1, v18
	v_and_b32_e32 v0, 0x118, v0
	v_or_b32_e32 v4, s16, v19
	s_mov_b32 m0, s80
	s_nop 0
	global_load_lds_dwordx4 v235, s[18:19]
	s_add_u32 s16, s24, 0x21020100
	v_lshl_or_b32 v4, v4, 6, v6
	s_addc_u32 s17, s25, 0
	s_mov_b32 m0, s81
	s_nop 0
	global_load_lds_dwordx4 v235, s[16:17]
	v_lshl_or_b32 v236, v3, 12, v4
	s_mov_b32 m0, s76
	s_nop 0
	global_load_lds_dwordx4 v236, s[10:11]
	s_add_u32 s10, s36, 0x29020000
	s_addc_u32 s11, s37, 0
	s_mov_b32 m0, s89
	s_nop 0
	global_load_lds_dwordx4 v236, s[10:11]
	s_add_u32 s10, s36, 0x29000100
	s_addc_u32 s11, s37, 0
	s_mov_b32 m0, s1
	s_nop 0
	global_load_lds_dwordx4 v236, s[10:11]
	s_add_u32 s10, s36, 0x29020100
	s_addc_u32 s11, s37, 0
	s_mov_b32 m0, s69
	s_nop 0
	global_load_lds_dwordx4 v236, s[10:11]
	s_add_u32 s10, s24, 0x21040100
	s_addc_u32 s11, s25, 0
	s_add_u32 s16, s36, 0x29040000
	s_addc_u32 s17, s37, 0
	s_mov_b32 m0, s29
	s_nop 0
	global_load_lds_dwordx4 v235, s[10:11]
	s_add_u32 s10, s24, 0x21060100
	s_addc_u32 s11, s25, 0
	s_mov_b32 m0, s88
	s_nop 0
	global_load_lds_dwordx4 v235, s[10:11]
	s_mov_b32 m0, s22
	s_nop 0
	global_load_lds_dwordx4 v236, s[16:17]
	s_add_u32 s10, s36, 0x29060000
	s_addc_u32 s11, s37, 0
	s_mov_b32 m0, s2
	s_nop 0
	global_load_lds_dwordx4 v236, s[10:11]
	s_add_u32 s10, s36, 0x29040100
	s_addc_u32 s11, s37, 0
	s_mov_b32 m0, s14
	s_nop 0
	global_load_lds_dwordx4 v236, s[10:11]
	s_add_u32 s10, s36, 0x29060100
	s_addc_u32 s11, s37, 0
	s_mov_b32 m0, s15
	s_nop 0
	global_load_lds_dwordx4 v236, s[10:11]
	s_waitcnt vmcnt(12)
	ds_write_b128 v234, v[192:195]
	ds_write_b128 v234, v[196:199] offset:1024
	ds_write_b128 v234, v[200:203] offset:2048
	ds_write_b128 v234, v[204:207] offset:3072
	v_and_b32_e32 v3, 0xf0, v5
	s_movk_i32 s10, 0x60
	v_bitop3_b32 v242, v184, v3, s10 bitop3:0x36
	s_movk_i32 s10, 0x80
	v_bitop3_b32 v243, v184, v3, s10 bitop3:0x36
	s_movk_i32 s10, 0xa0
	v_bitop3_b32 v244, v184, v3, s10 bitop3:0x36
	s_movk_i32 s10, 0xc0
	v_bitop3_b32 v245, v184, v3, s10 bitop3:0x36
	s_movk_i32 s10, 0xe0
	v_and_b32_e32 v1, 0xc0, v16
	s_waitcnt vmcnt(6)
	v_bitop3_b32 v246, v184, v3, s10 bitop3:0x36
	v_and_or_b32 v0, v2, 32, v0
	s_add_u32 s10, s12, s6
	s_waitcnt lgkmcnt(0)
	s_barrier
; #define LAS __attribute__((address_space(3)))
; __device__ __forceinline__ int v_rd_base(int lane) { return ((lane & 3) << 3) | (((lane >> 2) & 3) << 6) | (((lane >> 4) & 1) << 5) | (((lane >> 5) & 1) << 8); }
; __device__ __forceinline__ void attn_pass_dv256(const bf16_t* __restrict__ Qb, const bf16_t* __restrict__ Kh, const bf16_t* __restrict__ Vh, int qpos0,
;                                                 LAS unsigned char* lds, f32x16 (&o)[8], float& l_out, int wave_) {
;     ...
;   float m_reg = -1e30f, l_reg = 0;
; #pragma unroll
;   for (int d = 0; d < 8; ++d) o[d] = f32x16{};
;   bf16x8 qr[4];
;   LAS unsigned char* qf = lds + Q2_OFF + wid * 4096;
;   const bf16_t* Qw = Qb + (size_t)(wid * 32 + r32) * LDX + hi * 8;
; #pragma unroll
;   for (int d0 = 0; d0 < 4; ++d0) qr[d0] = *(const bf16x8*)(Qw + d0 * 16);
; #pragma unroll
;   for (int d0 = 4; d0 < 8; ++d0) *(LAS bf16x8*)(qf + ((d0 - 4) * 64 + lane) * 16) = *(const bf16x8*)(Qw + d0 * 16);
;   const unsigned ldsb = (unsigned)(uintptr_t)lds;
;   const unsigned vb0 = ldsb + V2_OFF + v_rd_base(lane);
;   const int krow = 4 * wid + (lane >> 4);
;   const unsigned voffK = (unsigned)(krow * (LDX * 2) + (((lane & 15) ^ (krow & 15)) << 4));
;   const int vst_ = 2 * wid + (lane >> 5), vkk = (vst_ >> 2) * 8 + ((lane >> 2) & 7), vk = (vkk & ~0xC) | ((vkk & 4) << 1) | ((vkk & 8) >> 1);
;   const unsigned voffV = (unsigned)(vk * (LDX * 2) + ((vst_ & 3) * 4 + (lane & 3)) * 16);
;   const int qw0 = qpos0 + wid * 32, qme = qw0 + r32;
;   constexpr int NT = SEQ / KVBLK;
	v_lshlrev_b32_e32 v4, 2, v19
	v_add3_u32 v247, v1, 0, v0
	s_addc_u32 s11, s13, s7
	v_add_u32_e32 v0, s31, v20
	v_mov_b32_e32 v14, v185
	v_mov_b32_e32 v15, v185
	v_bitop3_b32 v239, v184, v5, s40 bitop3:0x78
	v_bitop3_b32 v240, v184, v3, 32 bitop3:0x36
	v_bitop3_b32 v241, v184, v3, 64 bitop3:0x36
	s_add_u32 s12, s8, s6
	v_sub_u32_e32 v248, v4, v0
	v_mov_b32_e32 v0, v185
	v_mov_b32_e32 v1, v185
	v_mov_b32_e32 v2, v185
	v_mov_b32_e32 v3, v185
	v_mov_b32_e32 v4, v185
	v_mov_b32_e32 v5, v185
	v_mov_b32_e32 v6, v185
	v_mov_b32_e32 v7, v185
	v_mov_b32_e32 v8, v185
	v_mov_b32_e32 v9, v185
	v_mov_b32_e32 v10, v185
	v_mov_b32_e32 v11, v185
	v_mov_b32_e32 v12, v185
	v_mov_b32_e32 v13, v185
	v_mov_b64_e32 v[46:47], v[14:15]
	v_mov_b64_e32 v[62:63], v[14:15]
	v_lshl_add_u32 v237, v20, 8, s23
	v_cmp_gt_u32_e64 s[38:39], 32, v21
	v_lshl_add_u32 v238, v20, 2, s59
	s_addc_u32 s13, s9, s7
	s_mov_b32 s16, 0
	v_mov_b64_e32 v[44:45], v[12:13]
	v_mov_b64_e32 v[42:43], v[10:11]
	v_mov_b64_e32 v[40:41], v[8:9]
	v_mov_b64_e32 v[38:39], v[6:7]
	v_mov_b64_e32 v[36:37], v[4:5]
	v_mov_b64_e32 v[34:35], v[2:3]
	v_mov_b64_e32 v[32:33], v[0:1]
	v_mov_b64_e32 v[60:61], v[12:13]
	v_mov_b64_e32 v[58:59], v[10:11]
	v_mov_b64_e32 v[56:57], v[8:9]
	v_mov_b64_e32 v[54:55], v[6:7]
	v_mov_b64_e32 v[52:53], v[4:5]
	v_mov_b64_e32 v[50:51], v[2:3]
	v_mov_b64_e32 v[48:49], v[0:1]
	s_mov_b32 s17, 0
	v_mov_b32_e32 v16, 0
	v_mov_b32_e32 v17, v250
	v_mov_b32_e32 v18, v250
	v_mov_b32_e32 v19, v250
	v_mov_b32_e32 v20, v250
	v_mov_b32_e32 v21, v250
	v_mov_b32_e32 v68, v250
	v_mov_b32_e32 v69, v250
	v_mov_b32_e32 v70, v250
	v_mov_b32_e32 v71, v250
	v_mov_b32_e32 v72, v250
	v_mov_b32_e32 v73, v250
	v_mov_b32_e32 v74, v250
	v_mov_b32_e32 v75, v250
	v_mov_b32_e32 v76, v250
	v_mov_b32_e32 v77, v250
	v_mov_b32_e32 v78, v250
	v_mov_b32_e32 v79, v250
	v_mov_b32_e32 v80, 0
	v_mov_b32_e32 v81, v250
	v_mov_b32_e32 v82, v250
	v_mov_b32_e32 v83, v250
	v_mov_b32_e32 v84, v250
	v_mov_b32_e32 v85, v250
	v_mov_b32_e32 v86, v250
	v_mov_b32_e32 v87, v250
	v_mov_b32_e32 v88, v250
	v_mov_b32_e32 v89, v250
	v_mov_b32_e32 v90, v250
	v_mov_b32_e32 v91, v250
	v_mov_b32_e32 v92, v250
	v_mov_b32_e32 v93, v250
	v_mov_b32_e32 v94, v250
	v_mov_b32_e32 v95, v250
	v_mov_b32_e32 v96, 0
	v_mov_b32_e32 v97, v250
	v_mov_b32_e32 v98, v250
	v_mov_b32_e32 v99, v250
	v_mov_b32_e32 v100, v250
	v_mov_b32_e32 v101, v250
	v_mov_b32_e32 v102, v250
	v_mov_b32_e32 v103, v250
	v_mov_b32_e32 v104, v250
	v_mov_b32_e32 v105, v250
	v_mov_b32_e32 v106, v250
	v_mov_b32_e32 v107, v250
	v_mov_b32_e32 v108, v250
	v_mov_b32_e32 v109, v250
	v_mov_b32_e32 v110, v250
	v_mov_b32_e32 v111, v250
	v_mov_b32_e32 v112, 0
	v_mov_b32_e32 v113, v250
	v_mov_b32_e32 v114, v250
	v_mov_b32_e32 v115, v250
	v_mov_b32_e32 v116, v250
	v_mov_b32_e32 v117, v250
	v_mov_b32_e32 v118, v250
	v_mov_b32_e32 v119, v250
	v_mov_b32_e32 v120, v250
	v_mov_b32_e32 v121, v250
	v_mov_b32_e32 v122, v250
	v_mov_b32_e32 v123, v250
	v_mov_b32_e32 v124, v250
	v_mov_b32_e32 v125, v250
	v_mov_b32_e32 v126, v250
	v_mov_b32_e32 v127, v250
